# S5 pass B: each wave scans 8 consecutive chunks carrying the state (prologue only once per wave); prep weight-transpose tiles issue their 8 row loads + scale loads together
# speedup vs baseline: 1.0330x; 1.0233x over previous
; DI void prep_phase(const Params& p, unsigned char* smem) {
;     ...
;     __syncthreads();
;     {
;       const int n = tid >> 3, k0 = (tid & 7) * 8;
;       const bf16x8 o = pack8(tl[k0][n], tl[k0 + 1][n], tl[k0 + 2][n], tl[k0 + 3][n], tl[k0 + 4][n], tl[k0 + 5][n], tl[k0 + 6][n], tl[k0 + 7][n]);
;       *(bf16x8*)(jb.dst + (size_t)(nt * 32 + n) * jb.K + kt * 64 + k0) = o;
;     }
.LBB0_8:
.Lprep_tail:
	s_waitcnt lgkmcnt(0)
	s_barrier
	ds_read2_b32 v[6:7], v17 offset1:33
	ds_read2_b32 v[14:15], v17 offset0:66 offset1:99
	ds_read2_b32 v[22:23], v17 offset0:132 offset1:165
	ds_read2_b32 v[24:25], v17 offset0:198 offset1:231
	s_load_dwordx2 s[4:5], s[12:13], 0x118
	s_load_dword s14, s[12:13], 0x128
	s_waitcnt lgkmcnt(0)
	v_cvt_pk_bf16_f32 v12, v6, v7
	v_add_u32_e32 v6, s18, v16
	s_ashr_i32 s17, s16, 31
	s_add_i32 s23, s23, s68
	v_mad_i64_i32 v[6:7], s[12:13], s14, v6, 0
	v_lshl_add_u64 v[6:7], v[6:7], 1, s[4:5]
	v_lshl_add_u64 v[6:7], s[16:17], 1, v[6:7]
	v_cvt_pk_bf16_f32 v13, v14, v15
	v_cvt_pk_bf16_f32 v14, v22, v23
	v_cvt_pk_bf16_f32 v15, v24, v25
	v_lshl_add_u64 v[6:7], v[6:7], 0, v[4:5]
	s_cmp_ge_i32 s23, s11
	global_store_dwordx4 v[6:7], v[12:15], off
	s_cbranch_scc1 .LBB0_29

; DI void prep_phase(const Params& p, unsigned char* smem) {
;     ...
;   for (int tix = blockIdx.x; tix < p.ntile_total; tix += gridDim.x) {
;     int j = 0;
;     while (j + 1 < p.njobs && p.jobs[j + 1].tile0 <= tix) ++j;
;     const TJob& jb = p.jobs[j];
;     const int loc = tix - jb.tile0, ntn = jb.N / 32, kt = loc / ntn, nt = loc % ntn;
;     __syncthreads();
; #pragma unroll
;     for (int i = 0; i < 8; ++i) {
;       const int r = (tid >> 5) + 8 * i, c = tid & 31;
;       float v = jb.src[(size_t)(kt * 64 + r) * jb.N + nt * 32 + c];
;       if (jb.scale) v *= jb.scale[kt * 64 + r];
;       tl[r][c] = v;
;     }
.LBB0_13:
	s_mul_i32 s4, s19, 40
	s_mul_hi_u32 s5, s18, 40
	s_add_i32 s5, s5, s4
	s_mul_i32 s4, s18, 40
	v_readlane_b32 s12, v250, 0
	v_readlane_b32 s13, v250, 1
	s_add_u32 s12, s12, s4
	s_addc_u32 s13, s13, s5
	s_load_dwordx2 s[14:15], s[12:13], 0x12c
	s_waitcnt lgkmcnt(0)
	s_ashr_i32 s4, s14, 31
	s_lshr_b32 s4, s4, 27
	s_add_i32 s4, s14, s4
	s_ashr_i32 s16, s4, 5
	s_abs_i32 s17, s16
	v_cvt_f32_u32_e32 v6, s17
	s_sub_i32 s20, 0, s17
	s_sub_i32 s15, s23, s15
	s_abs_i32 s18, s15
	v_rcp_iflag_f32_e32 v6, v6
	s_xor_b32 s19, s15, s16
	s_ashr_i32 s19, s19, 31
	s_load_dwordx2 s[4:5], s[12:13], 0x110
	s_load_dwordx2 s[24:25], s[12:13], 0x120
	v_mul_f32_e32 v6, 0x4f7ffffe, v6
	v_cvt_u32_f32_e32 v6, v6
	s_waitcnt lgkmcnt(0)
	s_barrier
	v_readfirstlane_b32 s21, v6
	s_mul_i32 s20, s20, s21
	s_mul_hi_u32 s20, s21, s20
	s_add_i32 s21, s21, s20
	s_mul_hi_u32 s20, s18, s21
	s_mul_i32 s21, s20, s17
	s_sub_i32 s18, s18, s21
	s_add_i32 s26, s20, 1
	s_sub_i32 s21, s18, s17
	s_cmp_ge_u32 s18, s17
	s_cselect_b32 s20, s26, s20
	s_cselect_b32 s18, s21, s18
	s_add_i32 s21, s20, 1
	s_cmp_ge_u32 s18, s17
	s_cselect_b32 s17, s21, s20
	s_xor_b32 s17, s17, s19
	s_sub_i32 s17, s17, s19
	s_mul_i32 s16, s17, s16
	s_sub_i32 s15, s15, s16
	s_lshl_b32 s18, s15, 5
	s_ashr_i32 s19, s18, 31
	s_lshl_b32 s16, s17, 6
	s_lshl_b64 s[20:21], s[18:19], 2
	s_add_u32 s4, s4, s20
	s_addc_u32 s5, s5, s21
	v_add_u32_e32 v12, s16, v9
	v_lshl_add_u64 v[6:7], s[4:5], 0, v[2:3]
	v_mad_i64_i32 v[14:15], s[4:5], s14, v12, 0
	v_lshl_add_u64 v[14:15], v[14:15], 2, v[6:7]
	global_load_dword v30, v[14:15], off
	s_lshl_b32 s4, s14, 5
	s_mov_b32 s5, 0
	v_lshl_add_u64 v[22:23], v[14:15], 0, s[4:5]
	global_load_dword v31, v[22:23], off
	v_lshl_add_u64 v[22:23], v[22:23], 0, s[4:5]
	global_load_dword v32, v[22:23], off
	v_lshl_add_u64 v[22:23], v[22:23], 0, s[4:5]
	global_load_dword v33, v[22:23], off
	v_lshl_add_u64 v[22:23], v[22:23], 0, s[4:5]
	global_load_dword v34, v[22:23], off
	v_lshl_add_u64 v[22:23], v[22:23], 0, s[4:5]
	global_load_dword v35, v[22:23], off
	v_lshl_add_u64 v[22:23], v[22:23], 0, s[4:5]
	global_load_dword v36, v[22:23], off
	v_lshl_add_u64 v[22:23], v[22:23], 0, s[4:5]
	global_load_dword v37, v[22:23], off
	v_ashrrev_i32_e32 v13, 31, v12
	v_lshl_add_u64 v[14:15], v[12:13], 2, s[24:25]
	v_mov_b32_e32 v40, 1.0
	v_mov_b32_e32 v41, 1.0
	v_mov_b32_e32 v42, 1.0
	v_mov_b32_e32 v43, 1.0
	v_mov_b32_e32 v44, 1.0
	v_mov_b32_e32 v45, 1.0
	v_mov_b32_e32 v46, 1.0
	v_mov_b32_e32 v47, 1.0
	s_cmp_eq_u64 s[24:25], 0
	s_cbranch_scc1 .Lprep_noscale
	global_load_dword v40, v[14:15], off
	global_load_dword v41, v[14:15], off offset:32
	global_load_dword v42, v[14:15], off offset:64
	global_load_dword v43, v[14:15], off offset:96
	global_load_dword v44, v[14:15], off offset:128
	global_load_dword v45, v[14:15], off offset:160
	global_load_dword v46, v[14:15], off offset:192
	global_load_dword v47, v[14:15], off offset:224
.Lprep_noscale:
	s_waitcnt vmcnt(0)
	v_mul_f32_e32 v30, v30, v40
	v_mul_f32_e32 v31, v31, v41
	v_mul_f32_e32 v32, v32, v42
	v_mul_f32_e32 v33, v33, v43
	v_mul_f32_e32 v34, v34, v44
	v_mul_f32_e32 v35, v35, v45
	v_mul_f32_e32 v36, v36, v46
	v_mul_f32_e32 v37, v37, v47
	ds_write_b32 v18, v30
	ds_write_b32 v18, v31 offset:1056
	ds_write_b32 v18, v32 offset:2112
	ds_write_b32 v18, v33 offset:3168
	ds_write_b32 v18, v34 offset:4224
	ds_write_b32 v18, v35 offset:5280
	ds_write_b32 v18, v36 offset:6336
	ds_write_b32 v18, v37 offset:7392
	s_branch .Lprep_tail

; template <bool PASSB>
; DI void s5_item(const Params& p, int oi, int witem, float* wl  ) {
;     ...
;   const int bgi = witem >> 8, c = witem & 255, b = bgi >> 5, g = bgi & 31;
;   const int gp = g * 64 + lane;
;   const float lre = pre[gp * 2], lim = pre[gp * 2 + 1];
;   float bre[16], bim[16];
; #pragma unroll
;   for (int h = 0; h < 16; ++h) { bre[h] = pre[8192 + (g * 32 + h) * 64 + lane]; bim[h] = pre[8192 + (g * 32 + 16 + h) * 64 + lane]; }
;   const size_t tg0 = (size_t)b * L + c * 64;
; __global__ void __launch_bounds__(256, 2) fwd_mega(Params p) {
;     ...
;         case 10: { if (PHMASK & 256) for (int it = blockIdx.x; it < 4096; it += gridDim.x) s5_item<true>(p, li, it * 4 + wave, (float*)smem + wave * 2176); } break;
.LBB0_152:
	s_cmpk_eq_u32 s68, 0x200
	s_cbranch_scc0 .Ls5b_oldmap
	s_and_b32 s3, s2, 0x1ff
	s_lshl_b32 s3, s3, 2
	s_add_i32 s3, s3, s49
	s_lshl_b32 s3, s3, 3
	s_lshr_b32 s4, s2, 9
	s_add_i32 s4, s4, s3
	s_branch .Ls5b_mapdone

; template <bool PASSB>
; DI void s5_item(const Params& p, int oi, int witem, float* wl  ) {
;     ...
;   const int bgi = witem >> 8, c = witem & 255, b = bgi >> 5, g = bgi & 31;
;   const int gp = g * 64 + lane;
;   const float lre = pre[gp * 2], lim = pre[gp * 2 + 1];
;   float bre[16], bim[16];
; #pragma unroll
;   for (int h = 0; h < 16; ++h) { bre[h] = pre[8192 + (g * 32 + h) * 64 + lane]; bim[h] = pre[8192 + (g * 32 + 16 + h) * 64 + lane]; }
;   const size_t tg0 = (size_t)b * L + c * 64;
;   __builtin_amdgcn_wave_barrier();
; #pragma unroll
;   for (int i = 0; i < 4; ++i) {
;     const int idx = i * 64 + lane, tt = idx >> 2, q = idx & 3;
;     *(f32x4*)(wl + tt * 16 + q * 4) = *(const f32x4*)(us5 + (tg0 + tt) * 512 + g * 16 + q * 4);
;   }
;   __builtin_amdgcn_wave_barrier();
;   __builtin_amdgcn_s_waitcnt(0xc07f);
;   float xre = 0.f, xim = 0.f;
;   if (PASSB) {
;     const float Lre = pre[4096 + gp * 2], Lim = pre[4096 + gp * 2 + 1];
;     const float* Sp = S + (size_t)bgi * 256 * 128;
;     int cc = 0;
;     for (; cc + 8 <= c; cc += 8) {
.Ls5b_mapdone:
	v_mov_b32_e32 v7, v183
	s_ashr_i32 s24, s4, 8
	s_and_b32 s3, s24, 31
	s_waitcnt vmcnt(8)
	v_and_b32_e32 v16, 63, v7
	v_lshlrev_b32_e32 v0, 3, v16
	s_lshl_b32 s5, s3, 11
	v_lshl_or_b32 v176, s3, 9, v0
	v_or_b32_e32 v0, 0x2000, v16
	v_or_b32_e32 v1, 0x2400, v16
	s_or_b32 s25, s5, 64
	v_add_lshl_u32 v4, v0, s25, 2
	v_add_lshl_u32 v5, v1, s25, 2
	s_or_b32 s25, s5, 0x80
	v_add_lshl_u32 v6, v0, s25, 2
	s_waitcnt vmcnt(4)
	v_add_lshl_u32 v8, v1, s25, 2
	s_or_b32 s25, s5, 0xc0
	v_add_lshl_u32 v2, v0, s5, 2
	v_add_lshl_u32 v3, v1, s5, 2
	v_add_lshl_u32 v9, v0, s25, 2
	v_add_lshl_u32 v10, v1, s25, 2
	s_or_b32 s25, s5, 0x100
	global_load_dword v20, v2, s[40:41]
	global_load_dword v21, v3, s[40:41]
	global_load_dword v22, v4, s[40:41]
	global_load_dword v23, v5, s[40:41]
	global_load_dword v24, v6, s[40:41]
	global_load_dword v25, v8, s[40:41]
	global_load_dword v26, v9, s[40:41]
	global_load_dword v27, v10, s[40:41]
	v_add_lshl_u32 v2, v0, s25, 2
	v_add_lshl_u32 v3, v1, s25, 2
	s_or_b32 s25, s5, 0x140
	v_add_lshl_u32 v4, v0, s25, 2
	v_add_lshl_u32 v5, v1, s25, 2
	s_or_b32 s25, s5, 0x180
	v_add_lshl_u32 v6, v0, s25, 2
	v_add_lshl_u32 v8, v1, s25, 2
	s_or_b32 s25, s5, 0x1c0
	v_add_lshl_u32 v9, v0, s25, 2
	v_add_lshl_u32 v10, v1, s25, 2
	s_or_b32 s25, s5, 0x200
	global_load_dword v28, v2, s[40:41]
	global_load_dword v29, v3, s[40:41]
	global_load_dword v30, v4, s[40:41]
	global_load_dword v31, v5, s[40:41]
	global_load_dword v32, v6, s[40:41]
	global_load_dword v33, v8, s[40:41]
	global_load_dword v34, v9, s[40:41]
	global_load_dword v35, v10, s[40:41]
	v_add_lshl_u32 v2, v0, s25, 2
	v_add_lshl_u32 v3, v1, s25, 2
	s_or_b32 s25, s5, 0x240
	v_add_lshl_u32 v4, v0, s25, 2
	v_add_lshl_u32 v5, v1, s25, 2
	s_or_b32 s25, s5, 0x280
	v_add_lshl_u32 v6, v0, s25, 2
	v_add_lshl_u32 v8, v1, s25, 2
	s_or_b32 s25, s5, 0x2c0
	v_add_lshl_u32 v9, v0, s25, 2
	v_add_lshl_u32 v10, v1, s25, 2
	s_or_b32 s25, s5, 0x300
	global_load_dword v36, v2, s[40:41]
	global_load_dword v37, v3, s[40:41]
	global_load_dword v38, v4, s[40:41]
	global_load_dword v39, v5, s[40:41]
	global_load_dword v40, v6, s[40:41]
	global_load_dword v41, v8, s[40:41]
	global_load_dword v42, v9, s[40:41]
	global_load_dword v43, v10, s[40:41]
	v_add_lshl_u32 v2, v0, s25, 2
	v_add_lshl_u32 v3, v1, s25, 2
	s_or_b32 s25, s5, 0x340
	s_and_b32 s27, s4, 0xff
	v_add_lshl_u32 v4, v0, s25, 2
	v_add_lshl_u32 v5, v1, s25, 2
	s_or_b32 s25, s5, 0x380
	s_or_b32 s5, s5, 0x3c0
	s_ashr_i32 s4, s4, 13
	v_add_lshl_u32 v6, v0, s25, 2
	v_add_lshl_u32 v8, v1, s25, 2
	v_add_lshl_u32 v0, v0, s5, 2
	v_add_lshl_u32 v1, v1, s5, 2
	s_ashr_i32 s5, s4, 31
	s_lshl_b64 s[4:5], s[4:5], 14
	s_lshl_b32 s25, s27, 6
	s_or_b32 s4, s4, s25
	s_lshl_b32 s25, s3, 6
	global_load_dword v44, v2, s[40:41]
	global_load_dword v45, v3, s[40:41]
	global_load_dword v46, v4, s[40:41]
	global_load_dword v47, v5, s[40:41]
	global_load_dword v48, v6, s[40:41]
	global_load_dword v49, v8, s[40:41]
	global_load_dword v50, v0, s[40:41]
	global_load_dword v51, v1, s[40:41]
	s_add_u32 s30, s44, s25
	v_lshlrev_b32_e32 v0, 4, v7
	s_addc_u32 s31, s45, 0
	v_and_b32_e32 v4, 48, v0
	v_mov_b32_e32 v5, v177
	v_lshl_add_u64 v[0:1], s[30:31], 0, v[4:5]
	v_bfe_u32 v5, v7, 2, 4
	v_or_b32_e32 v2, s4, v5
	v_mov_b32_e32 v3, s5
	v_lshlrev_b64 v[8:9], 11, v[2:3]
	v_or_b32_e32 v2, 64, v16
	v_lshrrev_b32_e32 v6, 2, v2
	v_or_b32_e32 v2, s4, v6
	v_or_b32_e32 v17, 32, v5
	v_lshlrev_b64 v[10:11], 11, v[2:3]
	v_or_b32_e32 v2, s4, v17
	v_or_b32_e32 v58, 48, v5
	v_lshlrev_b64 v[12:13], 11, v[2:3]
	v_or_b32_e32 v2, s4, v58
	v_lshl_add_u64 v[8:9], v[0:1], 0, v[8:9]
	v_lshl_add_u64 v[10:11], v[0:1], 0, v[10:11]
	v_lshl_add_u64 v[12:13], v[0:1], 0, v[12:13]
	v_lshlrev_b64 v[2:3], 11, v[2:3]
	v_lshl_add_u64 v[18:19], v[0:1], 0, v[2:3]
	global_load_dwordx2 v[52:53], v176, s[40:41]
	global_load_dwordx4 v[0:3], v[8:9], off
	s_nop 0
	global_load_dwordx4 v[8:11], v[10:11], off
	s_nop 0
	global_load_dwordx4 v[12:15], v[12:13], off
	s_nop 0
	global_load_dwordx4 v[54:57], v[18:19], off
	v_add_u32_e32 v4, s42, v4
	v_lshl_add_u64 v[18:19], s[40:41], 0, v[176:177]
	v_lshl_add_u32 v5, v5, 6, v4
	v_lshl_add_u32 v6, v6, 6, v4
	v_lshl_add_u32 v17, v17, 6, v4
	v_lshl_add_u32 v4, v58, 6, v4
	s_ashr_i32 s25, s24, 31
	s_lshl_b64 s[24:25], s[24:25], 17
	s_cmp_lt_u32 s27, 8
	s_mov_b32 s30, 0
	s_waitcnt vmcnt(3)
	ds_write_b128 v5, v[0:3]
	s_waitcnt vmcnt(2)
	ds_write_b128 v6, v[8:11]
	s_waitcnt vmcnt(1)
	ds_write_b128 v17, v[12:15]
	s_waitcnt vmcnt(0)
	ds_write_b128 v4, v[54:57]
	v_add_co_u32_e32 v0, vcc, 0x4000, v18
	s_waitcnt lgkmcnt(0)
	s_nop 0
	v_addc_co_u32_e32 v1, vcc, 0, v19, vcc
	global_load_dwordx2 v[0:1], v[0:1], off
	s_cmpk_lt_i32 s2, 0x200
	s_cbranch_scc1 .Ls5b_prol
	s_cmpk_eq_u32 s68, 0x200
	s_cbranch_scc1 .Ls5b_carry
.Ls5b_prol:
	s_cmp_lt_u32 s27, 8
	s_cbranch_scc1 .LBB0_156
	s_add_u32 s30, s43, s24
	v_lshlrev_b32_e32 v176, 2, v16
	s_addc_u32 s31, s46, s25
	v_mov_b32_e32 v54, 0
	s_waitcnt vmcnt(0)
	v_pk_mov_b32 v[2:3], v[0:1], v[0:1] op_sel:[1,0]
	v_lshl_add_u64 v[4:5], s[30:31], 0, v[176:177]
	s_mov_b32 s30, 0
	v_mov_b32_e32 v55, v54

; template <bool PASSB>
; DI void s5_item(const Params& p, int oi, int witem, float* wl  ) {
;     ...
;   float xre = 0.f, xim = 0.f;
;   if (PASSB) {
;     const float Lre = pre[4096 + gp * 2], Lim = pre[4096 + gp * 2 + 1];
;     const float* Sp = S + (size_t)bgi * 256 * 128;
;     int cc = 0;
;     for (; cc + 8 <= c; cc += 8) {
;       float sr[8], si[8];
; #pragma unroll
;       for (int k = 0; k < 8; ++k) { sr[k] = Sp[(cc + k) * 128 + lane]; si[k] = Sp[(cc + k) * 128 + 64 + lane]; }
;       asm volatile("" ::: "memory"); __builtin_amdgcn_sched_barrier(0);
; #pragma unroll
;       for (int k = 0; k < 8; ++k) { const float nr = Lre * xre - Lim * xim + sr[k], ni = Lre * xim + Lim * xre + si[k]; xre = nr; xim = ni; }
;     }
;     for (; cc < c; ++cc) {
;       const float sr = Sp[cc * 128 + lane], si = Sp[cc * 128 + 64 + lane];
;       const float nr = Lre * xre - Lim * xim + sr, ni = Lre * xim + Lim * xre + si;
;       xre = nr; xim = ni;
;     }
;   }
.Ls5b_carry:
	v_mov_b32_e32 v54, v254
	v_mov_b32_e32 v55, v255
	s_lshl_b32 s28, s3, 4
	v_lshlrev_b32_e32 v60, 1, v16
	s_branch .LBB0_159

; DI bfr f2bf(float a) { return (bfr)(pk2(a, 0.f) & 0xffffu); }
; template <bool PASSB>
; DI void s5_item(const Params& p, int oi, int witem, float* wl  ) {
;     ...
;     for (int t16 = 0; t16 < 16; ++t16) {
;       const int tt = tb * 16 + t16;
;       float u[16];
; #pragma unroll
;       for (int q = 0; q < 4; ++q) { const f32x4 v = *(const f32x4*)(wl + tt * 16 + q * 4); u[q * 4] = v[0]; u[q * 4 + 1] = v[1]; u[q * 4 + 2] = v[2]; u[q * 4 + 3] = v[3]; }
;       float ar0 = 0.f, ar1 = 0.f, ai0 = 0.f, ai1 = 0.f;
; #pragma unroll
;       for (int h = 0; h < 16; h += 2) { ar0 += bre[h] * u[h]; ar1 += bre[h + 1] * u[h + 1]; ai0 += bim[h] * u[h]; ai1 += bim[h + 1] * u[h + 1]; }
;       const float ar = ar0 + ar1, ai = ai0 + ai1;
;       const float nr = lre * xre - lim * xim + ar, ni = lre * xim + lim * xre + ai;
;       xre = nr; xim = ni;
;       if (PASSB) { xl[t16 * 136 + lane] = f2bf(xre); xl[t16 * 136 + 64 + lane] = f2bf(xim); }
;     }
.LBB0_161:
	s_add_i32 s27, s24, s25
	v_mov_b32_e32 v61, s27
	ds_read_b128 v[66:69], v61
	ds_read_b128 v[70:73], v61 offset:16
	ds_read_b128 v[74:77], v61 offset:32
	ds_read_b128 v[78:81], v61 offset:48
	v_pk_mul_f32 v[82:83], v[58:59], v[54:55] op_sel:[0,1]
	s_waitcnt lgkmcnt(3)
	v_pk_fma_f32 v[84:85], v[20:21], v[66:67], 0 op_sel_hi:[1,0,0]
	v_pk_fma_f32 v[66:67], v[22:23], v[66:67], 0 op_sel:[0,1,0] op_sel_hi:[1,1,0]
	v_pk_fma_f32 v[84:85], v[24:25], v[68:69], v[84:85] op_sel_hi:[1,0,1]
	v_mov_b32_e32 v68, v69
	v_pk_fma_f32 v[66:67], v[26:27], v[68:69], v[66:67] op_sel_hi:[1,0,1]
	s_waitcnt lgkmcnt(2)
	v_pk_fma_f32 v[68:69], v[28:29], v[70:71], v[84:85] op_sel_hi:[1,0,1]
	v_pk_fma_f32 v[66:67], v[30:31], v[70:71], v[66:67] op_sel:[0,1,0]
	v_mov_b32_e32 v70, v73
	v_pk_fma_f32 v[68:69], v[32:33], v[72:73], v[68:69] op_sel_hi:[1,0,1]
	v_pk_fma_f32 v[66:67], v[34:35], v[70:71], v[66:67] op_sel_hi:[1,0,1]
	s_waitcnt lgkmcnt(1)
	v_pk_fma_f32 v[68:69], v[36:37], v[74:75], v[68:69] op_sel_hi:[1,0,1]
	v_pk_fma_f32 v[66:67], v[38:39], v[74:75], v[66:67] op_sel:[0,1,0]
	v_mov_b32_e32 v70, v77
	v_pk_fma_f32 v[68:69], v[40:41], v[76:77], v[68:69] op_sel_hi:[1,0,1]
	v_pk_fma_f32 v[66:67], v[42:43], v[70:71], v[66:67] op_sel_hi:[1,0,1]
	s_waitcnt lgkmcnt(0)
	v_pk_fma_f32 v[68:69], v[44:45], v[78:79], v[68:69] op_sel_hi:[1,0,1]
	v_pk_fma_f32 v[66:67], v[46:47], v[78:79], v[66:67] op_sel:[0,1,0]
	v_mov_b32_e32 v70, v81
	v_pk_fma_f32 v[68:69], v[48:49], v[80:81], v[68:69] op_sel_hi:[1,0,1]
	v_pk_fma_f32 v[66:67], v[50:51], v[70:71], v[66:67] op_sel_hi:[1,0,1]
	s_addk_i32 s25, 0x80
	v_pk_add_f32 v[66:67], v[68:69], v[66:67]
	v_pk_fma_f32 v[68:69], v[52:53], v[54:55], v[82:83] neg_lo:[0,0,1] neg_hi:[0,0,1]
	v_pk_fma_f32 v[54:55], v[52:53], v[54:55], v[82:83] op_sel_hi:[1,0,1]
	s_cmpk_lg_i32 s25, 0x400
	v_mov_b32_e32 v69, v55
	v_pk_add_f32 v[54:55], v[68:69], v[66:67]
	s_nop 0
	v_cvt_pk_bf16_f32 v66, v54, s0
	ds_write_b16 v60, v66
	v_cvt_pk_bf16_f32 v66, v55, s0
	ds_write_b16 v60, v66 offset:128
	ds_read_b128 v[66:69], v61 offset:64
	ds_read_b128 v[70:73], v61 offset:80
	ds_read_b128 v[74:77], v61 offset:96
	ds_read_b128 v[78:81], v61 offset:112
	v_pk_mul_f32 v[82:83], v[58:59], v[54:55] op_sel:[0,1]
	s_waitcnt lgkmcnt(3)
	v_pk_fma_f32 v[84:85], v[20:21], v[66:67], 0 op_sel_hi:[1,0,0]
	v_pk_fma_f32 v[66:67], v[22:23], v[66:67], 0 op_sel:[0,1,0] op_sel_hi:[1,1,0]
	v_pk_fma_f32 v[84:85], v[24:25], v[68:69], v[84:85] op_sel_hi:[1,0,1]
	v_mov_b32_e32 v68, v69
	v_pk_fma_f32 v[66:67], v[26:27], v[68:69], v[66:67] op_sel_hi:[1,0,1]
	s_waitcnt lgkmcnt(2)
	v_pk_fma_f32 v[68:69], v[28:29], v[70:71], v[84:85] op_sel_hi:[1,0,1]
	v_pk_fma_f32 v[66:67], v[30:31], v[70:71], v[66:67] op_sel:[0,1,0]
	v_mov_b32_e32 v70, v73
	v_pk_fma_f32 v[68:69], v[32:33], v[72:73], v[68:69] op_sel_hi:[1,0,1]
	v_pk_fma_f32 v[66:67], v[34:35], v[70:71], v[66:67] op_sel_hi:[1,0,1]
	s_waitcnt lgkmcnt(1)
	v_pk_fma_f32 v[68:69], v[36:37], v[74:75], v[68:69] op_sel_hi:[1,0,1]
	v_pk_fma_f32 v[66:67], v[38:39], v[74:75], v[66:67] op_sel:[0,1,0]
	v_mov_b32_e32 v70, v77
	v_pk_fma_f32 v[68:69], v[40:41], v[76:77], v[68:69] op_sel_hi:[1,0,1]
	v_pk_fma_f32 v[66:67], v[42:43], v[70:71], v[66:67] op_sel_hi:[1,0,1]
	s_waitcnt lgkmcnt(0)
	v_pk_fma_f32 v[68:69], v[44:45], v[78:79], v[68:69] op_sel_hi:[1,0,1]
	v_pk_fma_f32 v[66:67], v[46:47], v[78:79], v[66:67] op_sel:[0,1,0]
	v_mov_b32_e32 v70, v81
	v_pk_fma_f32 v[68:69], v[48:49], v[80:81], v[68:69] op_sel_hi:[1,0,1]
	v_pk_fma_f32 v[66:67], v[50:51], v[70:71], v[66:67] op_sel_hi:[1,0,1]
	s_nop 0
	v_pk_add_f32 v[66:67], v[68:69], v[66:67]
	v_pk_fma_f32 v[68:69], v[52:53], v[54:55], v[82:83] neg_lo:[0,0,1] neg_hi:[0,0,1]
	v_pk_fma_f32 v[54:55], v[52:53], v[54:55], v[82:83] op_sel_hi:[1,0,1]
	s_nop 0
	v_mov_b32_e32 v69, v55
	v_pk_add_f32 v[54:55], v[68:69], v[66:67]
	s_nop 0
	v_cvt_pk_bf16_f32 v61, v54, s0
	ds_write_b16 v60, v61 offset:272
	v_cvt_pk_bf16_f32 v61, v55, s0
	ds_write_b16 v60, v61 offset:400
	v_add_u32_e32 v60, 0x220, v60
	s_cbranch_scc1 .LBB0_161
; #define MFMA16(a, b, c) __builtin_amdgcn_mfma_f32_16x16x32_bf16((a), (b), (c), 0, 0, 0)
; DI u32x2 pk4(const f32x4& v) { u32x2 r = {pk2(v[0], v[1]), pk2(v[2], v[3])}; return r; }
; template <bool PASSB>
; DI void s5_item(const Params& p, int oi, int witem, float* wl  ) {
;     ...
;     if (PASSB) {
;       __builtin_amdgcn_wave_barrier();
;       f32x4 y = {0.f, 0.f, 0.f, 0.f};
; #pragma unroll
;       for (int ks = 0; ks < 4; ++ks) y = MFMA16(cf[ks], *(const bf16x8*)(xl + r16 * 136 + ks * 32 + quad * 8), y);
;       const int t = tb * 16 + r16;
;       const f32x4 uu = *(const f32x4*)(wl + t * 16 + quad * 4);
;       f32x4 o;
; #pragma unroll
;       for (int i = 0; i < 4; ++i) o[i] = gelu_tanh(y[i] + dsk4[i] * uu[i]);
;       *(u32x2*)(yg + (tg0 + t) * 512 + g * 16 + quad * 4) = pk4(o);
;       __builtin_amdgcn_wave_barrier();
;     }
;   }
	ds_read_b128 v[66:69], v64 offset:4096
	ds_read_b128 v[70:73], v64 offset:4160
	v_lshl_or_b32 v176, s3, 4, v62
	v_lshl_add_u32 v60, v176, 6, v63
	s_add_i32 s3, s3, 1
	s_waitcnt lgkmcnt(1)
	v_mfma_f32_16x16x32_bf16 v[66:69], v[0:3], v[66:69], 0
	s_addk_i32 s24, 0x400
	s_cmp_lg_u32 s3, 4
	s_waitcnt lgkmcnt(0)
	v_mfma_f32_16x16x32_bf16 v[66:69], v[4:7], v[70:73], v[66:69]
	ds_read_b128 v[70:73], v64 offset:4224
	s_waitcnt lgkmcnt(0)
	v_mfma_f32_16x16x32_bf16 v[66:69], v[8:11], v[70:73], v[66:69]
	ds_read_b128 v[70:73], v64 offset:4288
	s_waitcnt lgkmcnt(0)
	v_mfma_f32_16x16x32_bf16 v[66:69], v[12:15], v[70:73], v[66:69]
	ds_read_b128 v[70:73], v60
	s_waitcnt lgkmcnt(0)
	s_nop 5
	v_pk_fma_f32 v[66:67], v[16:17], v[70:71], v[66:67]
	v_pk_fma_f32 v[60:61], v[18:19], v[72:73], v[68:69]
	v_mul_f32_e32 v68, 0x3d372713, v66
	v_mul_f32_e32 v69, 0x3d372713, v67
	v_mul_f32_e32 v68, v66, v68
	v_mul_f32_e32 v69, v67, v69
	v_fma_f32 v68, v66, v68, v66
	v_fma_f32 v69, v67, v69, v67
	v_mul_f32_e32 v68, 0x3f4c422a, v68
	v_mul_f32_e32 v69, 0x3f4c422a, v69
	v_add_f32_e32 v68, v68, v68
	v_add_f32_e32 v69, v69, v69
	v_mul_f32_e32 v68, 0x3fb8aa3b, v68
	v_mul_f32_e32 v69, 0x3fb8aa3b, v69
	v_exp_f32_e32 v68, v68
	v_exp_f32_e32 v69, v69
	v_pk_mul_f32 v[66:67], v[66:67], 0.5 op_sel_hi:[1,0]
	v_pk_add_f32 v[68:69], v[68:69], 1.0 op_sel_hi:[1,0]
	s_nop 0
	v_div_scale_f32 v70, s[30:31], v69, v69, 2.0
	v_rcp_f32_e32 v71, v70
	s_nop 0
	v_fma_f32 v72, -v70, v71, 1.0
	v_fmac_f32_e32 v71, v72, v71
	v_div_scale_f32 v72, vcc, 2.0, v69, 2.0
	v_mul_f32_e32 v73, v72, v71
	v_fma_f32 v74, -v70, v73, v72
	v_fmac_f32_e32 v73, v74, v71
	v_fma_f32 v70, -v70, v73, v72
	v_div_fmas_f32 v70, v70, v71, v73
	v_div_fixup_f32 v69, v70, v69, 2.0
	v_div_scale_f32 v70, s[30:31], v68, v68, 2.0
	v_rcp_f32_e32 v71, v70
	s_nop 0
	v_fma_f32 v72, -v70, v71, 1.0
	v_fmac_f32_e32 v71, v72, v71
	v_div_scale_f32 v72, vcc, 2.0, v68, 2.0
	v_mul_f32_e32 v73, v72, v71
	v_fma_f32 v74, -v70, v73, v72
	v_fmac_f32_e32 v73, v74, v71
	v_fma_f32 v70, -v70, v73, v72
	v_div_fmas_f32 v70, v70, v71, v73
	v_div_fixup_f32 v68, v70, v68, 2.0
	v_pk_add_f32 v[68:69], v[68:69], 1.0 op_sel_hi:[1,0] neg_lo:[1,0] neg_hi:[1,0]
	s_nop 0
	v_pk_add_f32 v[68:69], v[68:69], 1.0 op_sel_hi:[1,0]
	s_nop 0
	v_pk_mul_f32 v[66:67], v[66:67], v[68:69]
	v_mul_f32_e32 v68, 0x3d372713, v60
	v_mul_f32_e32 v69, 0x3d372713, v61
	v_mul_f32_e32 v68, v60, v68
	v_mul_f32_e32 v69, v61, v69
	v_fma_f32 v68, v60, v68, v60
	v_fma_f32 v69, v61, v69, v61
	v_mul_f32_e32 v68, 0x3f4c422a, v68
	v_mul_f32_e32 v69, 0x3f4c422a, v69
	v_add_f32_e32 v68, v68, v68
	v_add_f32_e32 v69, v69, v69
	v_mul_f32_e32 v68, 0x3fb8aa3b, v68
	v_mul_f32_e32 v69, 0x3fb8aa3b, v69
	v_exp_f32_e32 v68, v68
	v_exp_f32_e32 v69, v69
	v_pk_mul_f32 v[60:61], v[60:61], 0.5 op_sel_hi:[1,0]
	v_cvt_pk_bf16_f32 v66, v66, v67
	v_pk_add_f32 v[68:69], v[68:69], 1.0 op_sel_hi:[1,0]
	s_nop 0
	v_div_scale_f32 v70, s[30:31], v69, v69, 2.0
	v_rcp_f32_e32 v71, v70
	s_nop 0
	v_fma_f32 v72, -v70, v71, 1.0
	v_fmac_f32_e32 v71, v72, v71
	v_div_scale_f32 v72, vcc, 2.0, v69, 2.0
	v_mul_f32_e32 v73, v72, v71
	v_fma_f32 v74, -v70, v73, v72
	v_fmac_f32_e32 v73, v74, v71
	v_fma_f32 v70, -v70, v73, v72
	v_div_fmas_f32 v70, v70, v71, v73
	v_div_fixup_f32 v69, v70, v69, 2.0
	v_div_scale_f32 v70, s[30:31], v68, v68, 2.0
	v_rcp_f32_e32 v71, v70
	s_nop 0
	v_fma_f32 v72, -v70, v71, 1.0
	v_fmac_f32_e32 v71, v72, v71
	v_div_scale_f32 v72, vcc, 2.0, v68, 2.0
	v_mul_f32_e32 v73, v72, v71
	v_fma_f32 v74, -v70, v73, v72
	v_fmac_f32_e32 v73, v74, v71
	v_fma_f32 v70, -v70, v73, v72
	v_div_fmas_f32 v70, v70, v71, v73
	v_div_fixup_f32 v68, v70, v68, 2.0
	v_pk_add_f32 v[68:69], v[68:69], 1.0 op_sel_hi:[1,0] neg_lo:[1,0] neg_hi:[1,0]
	s_nop 0
	v_pk_add_f32 v[68:69], v[68:69], 1.0 op_sel_hi:[1,0]
	s_nop 0
	v_pk_mul_f32 v[60:61], v[60:61], v[68:69]
	s_nop 0
	v_cvt_pk_bf16_f32 v67, v60, v61
	v_lshl_add_u64 v[60:61], s[4:5], 0, v[176:177]
	v_lshlrev_b64 v[60:61], 10, v[60:61]
	v_lshl_add_u64 v[60:61], v[56:57], 0, v[60:61]
	global_store_dwordx2 v[60:61], v[66:67], off
	s_cbranch_scc1 .LBB0_160
	v_mov_b32_e32 v254, v54
	v_mov_b32_e32 v255, v55
	s_add_i32 s2, s2, s68
	s_cmpk_gt_i32 s2, 0xfff
	s_cbranch_scc0 .LBB0_152

; __global__ void __launch_bounds__(256, 2) fwd_mega(Params p) {
;   __shared__ __attribute__((aligned(16))) unsigned char smem[56832];
	.amdhsa_kernel _Z8fwd_mega6Params
		.amdhsa_group_segment_fixed_size 77344
		.amdhsa_private_segment_fixed_size 0
		.amdhsa_kernarg_size 1576
		.amdhsa_user_sgpr_count 2
		.amdhsa_user_sgpr_dispatch_ptr 0
		.amdhsa_user_sgpr_queue_ptr 0
		.amdhsa_user_sgpr_kernarg_segment_ptr 1
		.amdhsa_user_sgpr_dispatch_id 0
		.amdhsa_user_sgpr_kernarg_preload_length 0
		.amdhsa_user_sgpr_kernarg_preload_offset 0
		.amdhsa_user_sgpr_private_segment_size 0
		.amdhsa_uses_dynamic_stack 0
		.amdhsa_enable_private_segment 0
		.amdhsa_system_sgpr_workgroup_id_x 1
		.amdhsa_system_sgpr_workgroup_id_y 0
		.amdhsa_system_sgpr_workgroup_id_z 0
		.amdhsa_system_sgpr_workgroup_info 0
		.amdhsa_system_vgpr_workitem_id 2
		.amdhsa_next_free_vgpr 256
		.amdhsa_next_free_sgpr 98
		.amdhsa_accum_offset 256
		.amdhsa_reserve_vcc 1
		.amdhsa_float_round_mode_32 0
		.amdhsa_float_round_mode_16_64 0
		.amdhsa_float_denorm_mode_32 3
		.amdhsa_float_denorm_mode_16_64 3
		.amdhsa_dx10_clamp 1
		.amdhsa_ieee_mode 1
		.amdhsa_fp16_overflow 0
		.amdhsa_tg_split 0
		.amdhsa_exception_fp_ieee_invalid_op 0
		.amdhsa_exception_fp_denorm_src 0
		.amdhsa_exception_fp_ieee_div_zero 0
		.amdhsa_exception_fp_ieee_overflow 0
		.amdhsa_exception_fp_ieee_underflow 0
		.amdhsa_exception_fp_ieee_inexact 0
		.amdhsa_exception_int_div_zero 0
	.end_amdhsa_kernel

; __global__ void __launch_bounds__(256, 2) fwd_mega(Params p) {
;   __shared__ __attribute__((aligned(16))) unsigned char smem[56832];
amdhsa.kernels:
  - .agpr_count:     0
    .args:
      - .offset:         0
        .size:           1320
        .value_kind:     by_value
      - .offset:         1320
        .size:           4
        .value_kind:     hidden_block_count_x
      - .offset:         1324
        .size:           4
        .value_kind:     hidden_block_count_y
      - .offset:         1328
        .size:           4
        .value_kind:     hidden_block_count_z
      - .offset:         1332
        .size:           2
        .value_kind:     hidden_group_size_x
      - .offset:         1334
        .size:           2
        .value_kind:     hidden_group_size_y
      - .offset:         1336
        .size:           2
        .value_kind:     hidden_group_size_z
      - .offset:         1338
        .size:           2
        .value_kind:     hidden_remainder_x
      - .offset:         1340
        .size:           2
        .value_kind:     hidden_remainder_y
      - .offset:         1342
        .size:           2
        .value_kind:     hidden_remainder_z
      - .offset:         1360
        .size:           8
        .value_kind:     hidden_global_offset_x
      - .offset:         1368
        .size:           8
        .value_kind:     hidden_global_offset_y
      - .offset:         1376
        .size:           8
        .value_kind:     hidden_global_offset_z
      - .offset:         1384
        .size:           2
        .value_kind:     hidden_grid_dims
      - .offset:         1408
        .size:           8
        .value_kind:     hidden_multigrid_sync_arg
    .group_segment_fixed_size: 77344
    .kernarg_segment_align: 8
    .kernarg_segment_size: 1576
    .language:       OpenCL C
    .language_version:
      - 2
      - 0
    .max_flat_workgroup_size: 256
    .name:           _Z8fwd_mega6Params
    .private_segment_fixed_size: 0
    .sgpr_count:     104
    .sgpr_spill_count: 425
    .symbol:         _Z8fwd_mega6Params.kd
    .uniform_work_group_size: 1
    .uses_dynamic_stack: false
    .vgpr_count:     256
    .vgpr_spill_count: 0
    .wavefront_size: 64
